# mode-0 residual epilogue rewritten like mode-1 (loads hoisted); rope-table L1 prefetch before the mixer in-projection epilogue
# speedup vs baseline: 1.0336x; 1.0033x over previous
; #define PG8_GAS __attribute__((address_space(1)))
; #define PG8_BAR __builtin_amdgcn_s_barrier()
;     __device__ __forceinline__ void operator()(const f32x4 (&acc)[2][2][4][2], const Unit& u, int wr, int wc, int fr, int fq) const {
;     ...
;                                 const f32x4 c0 = *(const PG8_GAS f32x4*)(rope + (size_t)r * 16), c1 = *(const PG8_GAS f32x4*)(rope + (size_t)r * 16 + 4);
;                                 const f32x4 s0 = *(const PG8_GAS f32x4*)(rope + (size_t)r * 16 + 8), s1 = *(const PG8_GAS f32x4*)(rope + (size_t)r * 16 + 12);
; template <class Epi, class Sched, bool ALIGN_EPI = false, bool SP2 = false>
; __device__ __forceinline__ void gemm_phase(PG8_LAS unsigned char* lds, const Gemm g, const Sched& S, const Epi& E, const int tid) {
;     ...
;         if constexpr (ALIGN_EPI) { if (wr == 0) PG8_BAR; }
;         if constexpr (!Epi::AFTER_DRAIN) { E(acc, cur, wr, wc, fr, fq); S.done(cur); }
.Lmix_exit:
	s_cmp_lt_u32 s0, 4
	s_cbranch_scc0 .Lmix_nopf
	v_and_b32_e32 v244, 0xffffffc0, v160
	v_lshrrev_b32_e32 v245, 5, v179
	v_and_b32_e32 v246, 31, v179
	v_lshlrev_b32_e32 v245, 7, v245
	v_lshl_add_u32 v245, v246, 1, v245
	v_add_u32_e32 v244, v244, v245
	v_lshl_add_u32 v244, s54, 8, v244
	v_lshlrev_b32_e32 v244, 6, v244
	global_load_dword v252, v244, s[48:49]
.Lmix_nopf:
	v_readlane_b32 s2, v255, 13
	v_readlane_b32 s3, v255, 14
	s_and_b64 vcc, exec, s[2:3]
	s_cbranch_vccz .LBB0_153
	s_barrier

; #define PG8_LAS __attribute__((address_space(3)))
; #define PG8_GAS __attribute__((address_space(1)))
;     __device__ __forceinline__ void operator()(const f32x4 (&acc)[2][2][4][2], const Unit& u, int wr, int wc, int fr, int fq) const {
;         const int b = u.pm >> 5, lane = fr + 16 * fq;
;         PG8_LAS unsigned char* sw = (PG8_LAS unsigned char*)(size_t)(scr + (unsigned)(wr * 4 + wc) * 2048u);
;         const int wrow = fr * 128, rrow = lane >> 3, rch = lane & 7;
;         f32x4 gt[2], lg[2], lb[2];
; #pragma unroll
;         for (int bj = 0; bj < 2; ++bj) {
;             const int c = u.pn * BM + bj * HALF + wc * 32 + 4 * rch;
;             gt[bj] = (*(const PG8_GAS f32x4*)(gate + (size_t)b * 9216 + c) + 1.f) * resw;
;             lg[bj] = (f32x4){1.f, 1.f, 1.f, 1.f}; lb[bj] = (f32x4){0.f, 0.f, 0.f, 0.f};
;             if (mode) { lg[bj] = *(const PG8_GAS f32x4*)(lng + c); lb[bj] = *(const PG8_GAS f32x4*)(lnb + c); }
;         }
; #pragma unroll
;         for (int ai = 0; ai < 2; ++ai)
; #pragma unroll
;             for (int m = 0; m < 4; ++m) {
;                 const int r0 = u.pm * BM + ai * HALF + wr * 64 + m * 16;
;                 f32x2 st2[2];
; #pragma unroll
;                 for (int s = 0; s < 2; ++s) { st2[s] = (f32x2){0.f, 1.f}; if (mode) st2[s] = *(const PG8_GAS f32x2*)(stats + 2 * (size_t)(r0 + 8 * s + rrow)); }
; #pragma unroll
;                 for (int bj = 0; bj < 2; ++bj) {
;                     const size_t off0 = (size_t)(r0 + rrow) * 1024 + u.pn * BM + bj * HALF + wc * 32 + 4 * rch;
;                     f32x4 xo[2];
; #pragma unroll
;                     for (int s = 0; s < 2; ++s) {
;                         if (!mode) xo[s] = *(const PG8_GAS f32x4*)(xin + off0 + (size_t)s * 8192);
;                         else { const u32x2 w = *(const PG8_GAS u32x2*)(Z + off0 + (size_t)s * 8192);
;                             xo[s] = (f32x4){__builtin_bit_cast(float, w.x << 16), __builtin_bit_cast(float, w.x & 0xffff0000u), __builtin_bit_cast(float, w.y << 16), __builtin_bit_cast(float, w.y & 0xffff0000u)}; }
;                     }
; #pragma unroll
;                     for (int n = 0; n < 2; ++n) *(PG8_LAS f32x4*)(sw + wrow + (((4 * n + fq) ^ (fr & 7)) << 4)) = acc[ai][bj][m][n];
;                     asm volatile("s_waitcnt lgkmcnt(0)" ::: "memory");
;                     f32x4 av[2];
; #pragma unroll
.Lres_m0:
	s_ashr_i32 s8, s67, 5
	s_mul_hi_i32 s9, s8, 0x9000
	s_mul_i32 s8, s8, 0x9000
	s_add_u32 s8, s51, s8
	s_addc_u32 s9, s56, s9
	s_lshl_b32 s32, s72, 10
	s_add_u32 s8, s8, s32
	s_addc_u32 s9, s9, 0
	v_lshlrev_b32_e32 v212, 2, v180
	global_load_dwordx4 v[32:35], v212, s[8:9]
	global_load_dwordx4 v[36:39], v212, s[8:9] offset:512
	s_lshl_b32 s54, s67, 8
	s_add_i32 s54, s54, s61
	s_lshl_b32 s55, s54, 12
	s_add_u32 s55, s55, s32
	s_add_u32 s24, s22, s55
	s_addc_u32 s25, s23, 0
	s_add_u32 s26, s24, 0x8000
	s_addc_u32 s27, s25, 0
	s_lshl_b32 s55, s54, 11
	s_lshl_b32 s32, s72, 9
	s_add_u32 s55, s55, s32
	s_add_u32 s30, s12, s55
	s_addc_u32 s31, s13, 0
	s_add_u32 s100, s30, 0x4000
	s_addc_u32 s101, s31, 0
	v_lshlrev_b32_e32 v203, 11, v202
	v_lshl_add_u32 v203, v180, 1, v203
	v_lshlrev_b32_e32 v209, 12, v202
	v_lshl_add_u32 v209, v180, 2, v209
	global_load_dwordx4 v[48:51], v209, s[24:25]
	global_load_dwordx4 v[52:55], v209, s[26:27]
	global_load_dwordx4 v[144:147], v209, s[24:25] offset:512
	global_load_dwordx4 v[148:151], v209, s[26:27] offset:512
	s_add_u32 s24, s24, 0x10000
	s_addc_u32 s25, s25, 0
	s_add_u32 s26, s26, 0x10000
	s_addc_u32 s27, s27, 0
	global_load_dwordx4 v[152:155], v209, s[24:25]
	global_load_dwordx4 v[156:159], v209, s[26:27]
	global_load_dwordx4 v[166:169], v209, s[24:25] offset:512
	global_load_dwordx4 v[188:191], v209, s[26:27] offset:512
	s_add_u32 s24, s24, 0x10000
	s_addc_u32 s25, s25, 0
	s_add_u32 s26, s26, 0x10000
	s_addc_u32 s27, s27, 0
	global_load_dwordx4 v[192:195], v209, s[24:25]
	global_load_dwordx4 v[196:199], v209, s[26:27]
	global_load_dwordx4 v[222:225], v209, s[24:25] offset:512
	global_load_dwordx4 v[226:229], v209, s[26:27] offset:512
	s_add_u32 s24, s24, 0x10000
	s_addc_u32 s25, s25, 0
	s_add_u32 s26, s26, 0x10000
	s_addc_u32 s27, s27, 0
	global_load_dwordx4 v[230:233], v209, s[24:25]
	global_load_dwordx4 v[234:237], v209, s[26:27]
	global_load_dwordx4 v[238:241], v209, s[24:25] offset:512
	global_load_dwordx4 v[242:245], v209, s[26:27] offset:512
	s_add_u32 s24, s24, 0x50000
	s_addc_u32 s25, s25, 0
	s_add_u32 s26, s26, 0x50000
	s_addc_u32 s27, s27, 0
	ds_write_b128 v219, v[140:143]
	ds_write_b128 v220, v[136:139]
	s_waitcnt lgkmcnt(0)
	ds_read_b128 v[140:143], v221
	ds_read_b128 v[136:139], v221 offset:1024
	s_waitcnt vmcnt(14)
	v_add_f32_e32 v32, 1.0, v32
	v_add_f32_e32 v33, 1.0, v33
	v_add_f32_e32 v34, 1.0, v34
	v_add_f32_e32 v35, 1.0, v35
	v_add_f32_e32 v36, 1.0, v36
	v_add_f32_e32 v37, 1.0, v37
	v_add_f32_e32 v38, 1.0, v38
	v_add_f32_e32 v39, 1.0, v39
	v_mul_f32_e32 v32, v162, v32
	v_mul_f32_e32 v33, v162, v33
	v_mul_f32_e32 v34, v162, v34
	v_mul_f32_e32 v35, v162, v35
	v_mul_f32_e32 v36, v162, v36
	v_mul_f32_e32 v37, v162, v37
	v_mul_f32_e32 v38, v162, v38
	v_mul_f32_e32 v39, v162, v39
	v_pk_mul_f32 v[48:49], v[48:49], s[46:47] op_sel_hi:[1,0]
	v_pk_mul_f32 v[50:51], v[50:51], s[46:47] op_sel_hi:[1,0]
	v_pk_mul_f32 v[52:53], v[52:53], s[46:47] op_sel_hi:[1,0]
	v_pk_mul_f32 v[54:55], v[54:55], s[46:47] op_sel_hi:[1,0]
	s_waitcnt lgkmcnt(0)
	ds_write_b128 v219, v[132:135]
	ds_write_b128 v220, v[128:131]
	v_pk_fma_f32 v[48:49], v[32:33], v[140:141], v[48:49]
	v_pk_fma_f32 v[50:51], v[34:35], v[142:143], v[50:51]
	v_cvt_pk_bf16_f32 v48, v48, v49
	v_cvt_pk_bf16_f32 v49, v50, v51
	global_store_dwordx2 v203, v[48:49], s[30:31]
	v_pk_fma_f32 v[52:53], v[32:33], v[136:137], v[52:53]
	v_pk_fma_f32 v[54:55], v[34:35], v[138:139], v[54:55]
	v_cvt_pk_bf16_f32 v52, v52, v53
	v_cvt_pk_bf16_f32 v53, v54, v55
	global_store_dwordx2 v203, v[52:53], s[100:101]
	global_load_dwordx4 v[140:143], v209, s[24:25]
	global_load_dwordx4 v[136:139], v209, s[26:27]
	s_waitcnt lgkmcnt(0)
	ds_read_b128 v[132:135], v221
	ds_read_b128 v[128:131], v221 offset:1024
	s_waitcnt vmcnt(16)
	v_pk_mul_f32 v[144:145], v[144:145], s[46:47] op_sel_hi:[1,0]
	v_pk_mul_f32 v[146:147], v[146:147], s[46:47] op_sel_hi:[1,0]
	v_pk_mul_f32 v[148:149], v[148:149], s[46:47] op_sel_hi:[1,0]
	v_pk_mul_f32 v[150:151], v[150:151], s[46:47] op_sel_hi:[1,0]
	s_waitcnt lgkmcnt(0)
	ds_write_b128 v219, v[124:127]
	ds_write_b128 v220, v[120:123]
	v_pk_fma_f32 v[144:145], v[36:37], v[132:133], v[144:145]
	v_pk_fma_f32 v[146:147], v[38:39], v[134:135], v[146:147]
	v_cvt_pk_bf16_f32 v144, v144, v145
	v_cvt_pk_bf16_f32 v145, v146, v147
	global_store_dwordx2 v203, v[144:145], s[30:31] offset:256
	v_pk_fma_f32 v[148:149], v[36:37], v[128:129], v[148:149]
	v_pk_fma_f32 v[150:151], v[38:39], v[130:131], v[150:151]
	v_cvt_pk_bf16_f32 v148, v148, v149
	v_cvt_pk_bf16_f32 v149, v150, v151
	global_store_dwordx2 v203, v[148:149], s[100:101] offset:256
	s_add_u32 s30, s30, 0x8000
	s_addc_u32 s31, s31, 0
	s_add_u32 s100, s100, 0x8000
	s_addc_u32 s101, s101, 0
	global_load_dwordx4 v[132:135], v209, s[24:25] offset:512
	global_load_dwordx4 v[128:131], v209, s[26:27] offset:512
	s_add_u32 s24, s24, 0x10000
	s_addc_u32 s25, s25, 0
	s_add_u32 s26, s26, 0x10000
	s_addc_u32 s27, s27, 0
	s_waitcnt lgkmcnt(0)
	ds_read_b128 v[124:127], v221
	ds_read_b128 v[120:123], v221 offset:1024
	s_waitcnt vmcnt(18)
	v_pk_mul_f32 v[152:153], v[152:153], s[46:47] op_sel_hi:[1,0]
	v_pk_mul_f32 v[154:155], v[154:155], s[46:47] op_sel_hi:[1,0]
	v_pk_mul_f32 v[156:157], v[156:157], s[46:47] op_sel_hi:[1,0]
	v_pk_mul_f32 v[158:159], v[158:159], s[46:47] op_sel_hi:[1,0]
	s_waitcnt lgkmcnt(0)
; #define PG8_LAS __attribute__((address_space(3)))
; __device__ __forceinline__ unsigned cvt_pk_bf16(float lo, float hi) { const f32x2c v = {lo, hi}; const bf16x2c b = __builtin_convertvector(v, bf16x2c); return __builtin_bit_cast(unsigned, b); }
;     __device__ __forceinline__ void operator()(const f32x4 (&acc)[2][2][4][2], const Unit& u, int wr, int wc, int fr, int fq) const {
;     ...
;                 const int r0 = u.pm * BM + ai * HALF + wr * 64 + m * 16;
;                 f32x2 st2[2];
; #pragma unroll
;                 for (int s = 0; s < 2; ++s) { st2[s] = (f32x2){0.f, 1.f}; if (mode) st2[s] = *(const PG8_GAS f32x2*)(stats + 2 * (size_t)(r0 + 8 * s + rrow)); }
; #pragma unroll
;                 for (int bj = 0; bj < 2; ++bj) {
;                     const size_t off0 = (size_t)(r0 + rrow) * 1024 + u.pn * BM + bj * HALF + wc * 32 + 4 * rch;
;                     f32x4 xo[2];
; #pragma unroll
;                     for (int s = 0; s < 2; ++s) {
;                         if (!mode) xo[s] = *(const PG8_GAS f32x4*)(xin + off0 + (size_t)s * 8192);
;                         else { const u32x2 w = *(const PG8_GAS u32x2*)(Z + off0 + (size_t)s * 8192);
;                             xo[s] = (f32x4){__builtin_bit_cast(float, w.x << 16), __builtin_bit_cast(float, w.x & 0xffff0000u), __builtin_bit_cast(float, w.y << 16), __builtin_bit_cast(float, w.y & 0xffff0000u)}; }
;                     }
; #pragma unroll
;                     for (int n = 0; n < 2; ++n) *(PG8_LAS f32x4*)(sw + wrow + (((4 * n + fq) ^ (fr & 7)) << 4)) = acc[ai][bj][m][n];
;                     asm volatile("s_waitcnt lgkmcnt(0)" ::: "memory");
;                     f32x4 av[2];
; #pragma unroll
;                     for (int s = 0; s < 2; ++s) av[s] = *(const PG8_LAS f32x4*)(sw + (8 * s + rrow) * 128 + ((rch ^ ((8 * s + rrow) & 7)) << 4));
;                     asm volatile("s_waitcnt lgkmcnt(0)" ::: "memory");
; #pragma unroll
;                     for (int s = 0; s < 2; ++s) {
;                         f32x4 xv = xo[s];
;                         if (mode) xv = (xv - st2[s].x) * st2[s].y * lg[bj] + lb[bj];
;                         const f32x4 zz = xv * alpha + gt[bj] * av[s];
;                         u32x2 zp; zp.x = cvt_pk_bf16(zz.x, zz.y); zp.y = cvt_pk_bf16(zz.z, zz.w);
;                         *(PG8_GAS u32x2*)(Z + off0 + (size_t)s * 8192) = zp;
;                     }
	ds_write_b128 v219, v[116:119]
	ds_write_b128 v220, v[112:115]
	v_pk_fma_f32 v[152:153], v[32:33], v[124:125], v[152:153]
	v_pk_fma_f32 v[154:155], v[34:35], v[126:127], v[154:155]
	v_cvt_pk_bf16_f32 v152, v152, v153
	v_cvt_pk_bf16_f32 v153, v154, v155
	global_store_dwordx2 v203, v[152:153], s[30:31]
	v_pk_fma_f32 v[156:157], v[32:33], v[120:121], v[156:157]
	v_pk_fma_f32 v[158:159], v[34:35], v[122:123], v[158:159]
	v_cvt_pk_bf16_f32 v156, v156, v157
	v_cvt_pk_bf16_f32 v157, v158, v159
	global_store_dwordx2 v203, v[156:157], s[100:101]
	global_load_dwordx4 v[124:127], v209, s[24:25]
	global_load_dwordx4 v[120:123], v209, s[26:27]
	s_waitcnt lgkmcnt(0)
	ds_read_b128 v[116:119], v221
	ds_read_b128 v[112:115], v221 offset:1024
	s_waitcnt vmcnt(20)
	v_pk_mul_f32 v[166:167], v[166:167], s[46:47] op_sel_hi:[1,0]
	v_pk_mul_f32 v[168:169], v[168:169], s[46:47] op_sel_hi:[1,0]
	v_pk_mul_f32 v[188:189], v[188:189], s[46:47] op_sel_hi:[1,0]
	v_pk_mul_f32 v[190:191], v[190:191], s[46:47] op_sel_hi:[1,0]
	s_waitcnt lgkmcnt(0)
	ds_write_b128 v219, v[108:111]
	ds_write_b128 v220, v[104:107]
	v_pk_fma_f32 v[166:167], v[36:37], v[116:117], v[166:167]
	v_pk_fma_f32 v[168:169], v[38:39], v[118:119], v[168:169]
	v_cvt_pk_bf16_f32 v166, v166, v167
	v_cvt_pk_bf16_f32 v167, v168, v169
	global_store_dwordx2 v203, v[166:167], s[30:31] offset:256
	v_pk_fma_f32 v[188:189], v[36:37], v[112:113], v[188:189]
	v_pk_fma_f32 v[190:191], v[38:39], v[114:115], v[190:191]
	v_cvt_pk_bf16_f32 v188, v188, v189
	v_cvt_pk_bf16_f32 v189, v190, v191
	global_store_dwordx2 v203, v[188:189], s[100:101] offset:256
	s_add_u32 s30, s30, 0x8000
	s_addc_u32 s31, s31, 0
	s_add_u32 s100, s100, 0x8000
	s_addc_u32 s101, s101, 0
	global_load_dwordx4 v[116:119], v209, s[24:25] offset:512
	global_load_dwordx4 v[112:115], v209, s[26:27] offset:512
	s_add_u32 s24, s24, 0x10000
	s_addc_u32 s25, s25, 0
	s_add_u32 s26, s26, 0x10000
	s_addc_u32 s27, s27, 0
	s_waitcnt lgkmcnt(0)
	ds_read_b128 v[108:111], v221
	ds_read_b128 v[104:107], v221 offset:1024
	s_waitcnt vmcnt(22)
	v_pk_mul_f32 v[192:193], v[192:193], s[46:47] op_sel_hi:[1,0]
	v_pk_mul_f32 v[194:195], v[194:195], s[46:47] op_sel_hi:[1,0]
	v_pk_mul_f32 v[196:197], v[196:197], s[46:47] op_sel_hi:[1,0]
	v_pk_mul_f32 v[198:199], v[198:199], s[46:47] op_sel_hi:[1,0]
	s_waitcnt lgkmcnt(0)
	ds_write_b128 v219, v[100:103]
	ds_write_b128 v220, v[96:99]
	v_pk_fma_f32 v[192:193], v[32:33], v[108:109], v[192:193]
	v_pk_fma_f32 v[194:195], v[34:35], v[110:111], v[194:195]
	v_cvt_pk_bf16_f32 v192, v192, v193
	v_cvt_pk_bf16_f32 v193, v194, v195
	global_store_dwordx2 v203, v[192:193], s[30:31]
	v_pk_fma_f32 v[196:197], v[32:33], v[104:105], v[196:197]
	v_pk_fma_f32 v[198:199], v[34:35], v[106:107], v[198:199]
	v_cvt_pk_bf16_f32 v196, v196, v197
	v_cvt_pk_bf16_f32 v197, v198, v199
	global_store_dwordx2 v203, v[196:197], s[100:101]
	global_load_dwordx4 v[108:111], v209, s[24:25]
	global_load_dwordx4 v[104:107], v209, s[26:27]
	s_waitcnt lgkmcnt(0)
	ds_read_b128 v[100:103], v221
	ds_read_b128 v[96:99], v221 offset:1024
	s_waitcnt vmcnt(24)
	v_pk_mul_f32 v[222:223], v[222:223], s[46:47] op_sel_hi:[1,0]
	v_pk_mul_f32 v[224:225], v[224:225], s[46:47] op_sel_hi:[1,0]
	v_pk_mul_f32 v[226:227], v[226:227], s[46:47] op_sel_hi:[1,0]
	v_pk_mul_f32 v[228:229], v[228:229], s[46:47] op_sel_hi:[1,0]
	s_waitcnt lgkmcnt(0)
	ds_write_b128 v219, v[92:95]
	ds_write_b128 v220, v[88:91]
	v_pk_fma_f32 v[222:223], v[36:37], v[100:101], v[222:223]
	v_pk_fma_f32 v[224:225], v[38:39], v[102:103], v[224:225]
	v_cvt_pk_bf16_f32 v222, v222, v223
	v_cvt_pk_bf16_f32 v223, v224, v225
	global_store_dwordx2 v203, v[222:223], s[30:31] offset:256
	v_pk_fma_f32 v[226:227], v[36:37], v[96:97], v[226:227]
	v_pk_fma_f32 v[228:229], v[38:39], v[98:99], v[228:229]
	v_cvt_pk_bf16_f32 v226, v226, v227
	v_cvt_pk_bf16_f32 v227, v228, v229
	global_store_dwordx2 v203, v[226:227], s[100:101] offset:256
	s_add_u32 s30, s30, 0x8000
	s_addc_u32 s31, s31, 0
	s_add_u32 s100, s100, 0x8000
	s_addc_u32 s101, s101, 0
	global_load_dwordx4 v[100:103], v209, s[24:25] offset:512
	global_load_dwordx4 v[96:99], v209, s[26:27] offset:512
	s_add_u32 s24, s24, 0x10000
	s_addc_u32 s25, s25, 0
	s_add_u32 s26, s26, 0x10000
	s_addc_u32 s27, s27, 0
	s_waitcnt lgkmcnt(0)
	ds_read_b128 v[92:95], v221
	ds_read_b128 v[88:91], v221 offset:1024
	s_waitcnt vmcnt(26)
	v_pk_mul_f32 v[230:231], v[230:231], s[46:47] op_sel_hi:[1,0]
	v_pk_mul_f32 v[232:233], v[232:233], s[46:47] op_sel_hi:[1,0]
	v_pk_mul_f32 v[234:235], v[234:235], s[46:47] op_sel_hi:[1,0]
	v_pk_mul_f32 v[236:237], v[236:237], s[46:47] op_sel_hi:[1,0]
	s_waitcnt lgkmcnt(0)
	ds_write_b128 v219, v[84:87]
	ds_write_b128 v220, v[80:83]
	v_pk_fma_f32 v[230:231], v[32:33], v[92:93], v[230:231]
	v_pk_fma_f32 v[232:233], v[34:35], v[94:95], v[232:233]
	v_cvt_pk_bf16_f32 v230, v230, v231
	v_cvt_pk_bf16_f32 v231, v232, v233
	global_store_dwordx2 v203, v[230:231], s[30:31]
	v_pk_fma_f32 v[234:235], v[32:33], v[88:89], v[234:235]
	v_pk_fma_f32 v[236:237], v[34:35], v[90:91], v[236:237]
	v_cvt_pk_bf16_f32 v234, v234, v235
	v_cvt_pk_bf16_f32 v235, v236, v237
	global_store_dwordx2 v203, v[234:235], s[100:101]
	global_load_dwordx4 v[92:95], v209, s[24:25]
	global_load_dwordx4 v[88:91], v209, s[26:27]
	s_waitcnt lgkmcnt(0)
	ds_read_b128 v[84:87], v221
	ds_read_b128 v[80:83], v221 offset:1024
	s_waitcnt vmcnt(28)
	v_pk_mul_f32 v[238:239], v[238:239], s[46:47] op_sel_hi:[1,0]
	v_pk_mul_f32 v[240:241], v[240:241], s[46:47] op_sel_hi:[1,0]
	v_pk_mul_f32 v[242:243], v[242:243], s[46:47] op_sel_hi:[1,0]
	v_pk_mul_f32 v[244:245], v[244:245], s[46:47] op_sel_hi:[1,0]
	s_waitcnt lgkmcnt(0)
; #define PG8_LAS __attribute__((address_space(3)))
; __device__ __forceinline__ unsigned cvt_pk_bf16(float lo, float hi) { const f32x2c v = {lo, hi}; const bf16x2c b = __builtin_convertvector(v, bf16x2c); return __builtin_bit_cast(unsigned, b); }
;     __device__ __forceinline__ void operator()(const f32x4 (&acc)[2][2][4][2], const Unit& u, int wr, int wc, int fr, int fq) const {
;     ...
;                 const int r0 = u.pm * BM + ai * HALF + wr * 64 + m * 16;
;                 f32x2 st2[2];
; #pragma unroll
;                 for (int s = 0; s < 2; ++s) { st2[s] = (f32x2){0.f, 1.f}; if (mode) st2[s] = *(const PG8_GAS f32x2*)(stats + 2 * (size_t)(r0 + 8 * s + rrow)); }
; #pragma unroll
;                 for (int bj = 0; bj < 2; ++bj) {
;                     const size_t off0 = (size_t)(r0 + rrow) * 1024 + u.pn * BM + bj * HALF + wc * 32 + 4 * rch;
;                     f32x4 xo[2];
; #pragma unroll
;                     for (int s = 0; s < 2; ++s) {
;                         if (!mode) xo[s] = *(const PG8_GAS f32x4*)(xin + off0 + (size_t)s * 8192);
;                         else { const u32x2 w = *(const PG8_GAS u32x2*)(Z + off0 + (size_t)s * 8192);
;                             xo[s] = (f32x4){__builtin_bit_cast(float, w.x << 16), __builtin_bit_cast(float, w.x & 0xffff0000u), __builtin_bit_cast(float, w.y << 16), __builtin_bit_cast(float, w.y & 0xffff0000u)}; }
;                     }
; #pragma unroll
;                     for (int n = 0; n < 2; ++n) *(PG8_LAS f32x4*)(sw + wrow + (((4 * n + fq) ^ (fr & 7)) << 4)) = acc[ai][bj][m][n];
;                     asm volatile("s_waitcnt lgkmcnt(0)" ::: "memory");
;                     f32x4 av[2];
; #pragma unroll
;                     for (int s = 0; s < 2; ++s) av[s] = *(const PG8_LAS f32x4*)(sw + (8 * s + rrow) * 128 + ((rch ^ ((8 * s + rrow) & 7)) << 4));
;                     asm volatile("s_waitcnt lgkmcnt(0)" ::: "memory");
; #pragma unroll
;                     for (int s = 0; s < 2; ++s) {
;                         f32x4 xv = xo[s];
;                         if (mode) xv = (xv - st2[s].x) * st2[s].y * lg[bj] + lb[bj];
;                         const f32x4 zz = xv * alpha + gt[bj] * av[s];
;                         u32x2 zp; zp.x = cvt_pk_bf16(zz.x, zz.y); zp.y = cvt_pk_bf16(zz.z, zz.w);
;                         *(PG8_GAS u32x2*)(Z + off0 + (size_t)s * 8192) = zp;
;                     }
	ds_write_b128 v219, v[76:79]
	ds_write_b128 v220, v[72:75]
	v_pk_fma_f32 v[238:239], v[36:37], v[84:85], v[238:239]
	v_pk_fma_f32 v[240:241], v[38:39], v[86:87], v[240:241]
	v_cvt_pk_bf16_f32 v238, v238, v239
	v_cvt_pk_bf16_f32 v239, v240, v241
	global_store_dwordx2 v203, v[238:239], s[30:31] offset:256
	v_pk_fma_f32 v[242:243], v[36:37], v[80:81], v[242:243]
	v_pk_fma_f32 v[244:245], v[38:39], v[82:83], v[244:245]
	v_cvt_pk_bf16_f32 v242, v242, v243
	v_cvt_pk_bf16_f32 v243, v244, v245
	global_store_dwordx2 v203, v[242:243], s[100:101] offset:256
	s_add_u32 s30, s30, 0x28000
	s_addc_u32 s31, s31, 0
	s_add_u32 s100, s100, 0x28000
	s_addc_u32 s101, s101, 0
	global_load_dwordx4 v[84:87], v209, s[24:25] offset:512
	global_load_dwordx4 v[80:83], v209, s[26:27] offset:512
	s_waitcnt lgkmcnt(0)
	ds_read_b128 v[76:79], v221
	ds_read_b128 v[72:75], v221 offset:1024
	s_waitcnt vmcnt(28)
	v_pk_mul_f32 v[140:141], v[140:141], s[46:47] op_sel_hi:[1,0]
	v_pk_mul_f32 v[142:143], v[142:143], s[46:47] op_sel_hi:[1,0]
	v_pk_mul_f32 v[136:137], v[136:137], s[46:47] op_sel_hi:[1,0]
	v_pk_mul_f32 v[138:139], v[138:139], s[46:47] op_sel_hi:[1,0]
	s_waitcnt lgkmcnt(0)
	ds_write_b128 v219, v[68:71]
	ds_write_b128 v220, v[64:67]
	v_pk_fma_f32 v[140:141], v[32:33], v[76:77], v[140:141]
	v_pk_fma_f32 v[142:143], v[34:35], v[78:79], v[142:143]
	v_cvt_pk_bf16_f32 v140, v140, v141
	v_cvt_pk_bf16_f32 v141, v142, v143
	global_store_dwordx2 v203, v[140:141], s[30:31]
	v_pk_fma_f32 v[136:137], v[32:33], v[72:73], v[136:137]
	v_pk_fma_f32 v[138:139], v[34:35], v[74:75], v[138:139]
	v_cvt_pk_bf16_f32 v136, v136, v137
	v_cvt_pk_bf16_f32 v137, v138, v139
	global_store_dwordx2 v203, v[136:137], s[100:101]
	s_waitcnt lgkmcnt(0)
	ds_read_b128 v[68:71], v221
	ds_read_b128 v[64:67], v221 offset:1024
	s_waitcnt vmcnt(26)
	v_pk_mul_f32 v[132:133], v[132:133], s[46:47] op_sel_hi:[1,0]
	v_pk_mul_f32 v[134:135], v[134:135], s[46:47] op_sel_hi:[1,0]
	v_pk_mul_f32 v[128:129], v[128:129], s[46:47] op_sel_hi:[1,0]
	v_pk_mul_f32 v[130:131], v[130:131], s[46:47] op_sel_hi:[1,0]
	s_waitcnt lgkmcnt(0)
	ds_write_b128 v219, v[60:63]
	ds_write_b128 v220, v[56:59]
	v_pk_fma_f32 v[132:133], v[36:37], v[68:69], v[132:133]
	v_pk_fma_f32 v[134:135], v[38:39], v[70:71], v[134:135]
	v_cvt_pk_bf16_f32 v132, v132, v133
	v_cvt_pk_bf16_f32 v133, v134, v135
	global_store_dwordx2 v203, v[132:133], s[30:31] offset:256
	v_pk_fma_f32 v[128:129], v[36:37], v[64:65], v[128:129]
	v_pk_fma_f32 v[130:131], v[38:39], v[66:67], v[130:131]
	v_cvt_pk_bf16_f32 v128, v128, v129
	v_cvt_pk_bf16_f32 v129, v130, v131
	global_store_dwordx2 v203, v[128:129], s[100:101] offset:256
	s_add_u32 s30, s30, 0x8000
	s_addc_u32 s31, s31, 0
	s_add_u32 s100, s100, 0x8000
	s_addc_u32 s101, s101, 0
	s_waitcnt lgkmcnt(0)
	ds_read_b128 v[60:63], v221
	ds_read_b128 v[56:59], v221 offset:1024
	s_waitcnt vmcnt(24)
	v_pk_mul_f32 v[124:125], v[124:125], s[46:47] op_sel_hi:[1,0]
	v_pk_mul_f32 v[126:127], v[126:127], s[46:47] op_sel_hi:[1,0]
	v_pk_mul_f32 v[120:121], v[120:121], s[46:47] op_sel_hi:[1,0]
	v_pk_mul_f32 v[122:123], v[122:123], s[46:47] op_sel_hi:[1,0]
	s_waitcnt lgkmcnt(0)
	ds_write_b128 v219, v[44:47]
	ds_write_b128 v220, v[40:43]
	v_pk_fma_f32 v[124:125], v[32:33], v[60:61], v[124:125]
	v_pk_fma_f32 v[126:127], v[34:35], v[62:63], v[126:127]
	v_cvt_pk_bf16_f32 v124, v124, v125
	v_cvt_pk_bf16_f32 v125, v126, v127
	global_store_dwordx2 v203, v[124:125], s[30:31]
	v_pk_fma_f32 v[120:121], v[32:33], v[56:57], v[120:121]
	v_pk_fma_f32 v[122:123], v[34:35], v[58:59], v[122:123]
	v_cvt_pk_bf16_f32 v120, v120, v121
	v_cvt_pk_bf16_f32 v121, v122, v123
	global_store_dwordx2 v203, v[120:121], s[100:101]
	s_waitcnt lgkmcnt(0)
	ds_read_b128 v[44:47], v221
	ds_read_b128 v[40:43], v221 offset:1024
	s_waitcnt vmcnt(22)
	v_pk_mul_f32 v[116:117], v[116:117], s[46:47] op_sel_hi:[1,0]
	v_pk_mul_f32 v[118:119], v[118:119], s[46:47] op_sel_hi:[1,0]
	v_pk_mul_f32 v[112:113], v[112:113], s[46:47] op_sel_hi:[1,0]
	v_pk_mul_f32 v[114:115], v[114:115], s[46:47] op_sel_hi:[1,0]
	s_waitcnt lgkmcnt(0)
;     __device__ __forceinline__ void operator()(const f32x4 (&acc)[2][2][4][2], const Unit& u, int wr, int wc, int fr, int fq) const {
;     ...
;                 const int r0 = u.pm * BM + ai * HALF + wr * 64 + m * 16;
;                 f32x2 st2[2];
; #pragma unroll
;                 for (int s = 0; s < 2; ++s) { st2[s] = (f32x2){0.f, 1.f}; if (mode) st2[s] = *(const PG8_GAS f32x2*)(stats + 2 * (size_t)(r0 + 8 * s + rrow)); }
; #pragma unroll
;                 for (int bj = 0; bj < 2; ++bj) {
;                     const size_t off0 = (size_t)(r0 + rrow) * 1024 + u.pn * BM + bj * HALF + wc * 32 + 4 * rch;
;                     f32x4 xo[2];
; #pragma unroll
;                     for (int s = 0; s < 2; ++s) {
;                         if (!mode) xo[s] = *(const PG8_GAS f32x4*)(xin + off0 + (size_t)s * 8192);
;                         else { const u32x2 w = *(const PG8_GAS u32x2*)(Z + off0 + (size_t)s * 8192);
;                             xo[s] = (f32x4){__builtin_bit_cast(float, w.x << 16), __builtin_bit_cast(float, w.x & 0xffff0000u), __builtin_bit_cast(float, w.y << 16), __builtin_bit_cast(float, w.y & 0xffff0000u)}; }
;                     }
; #pragma unroll
;                     for (int n = 0; n < 2; ++n) *(PG8_LAS f32x4*)(sw + wrow + (((4 * n + fq) ^ (fr & 7)) << 4)) = acc[ai][bj][m][n];
;                     asm volatile("s_waitcnt lgkmcnt(0)" ::: "memory");
;                     f32x4 av[2];
; #pragma unroll
;                     for (int s = 0; s < 2; ++s) av[s] = *(const PG8_LAS f32x4*)(sw + (8 * s + rrow) * 128 + ((rch ^ ((8 * s + rrow) & 7)) << 4));
;                     asm volatile("s_waitcnt lgkmcnt(0)" ::: "memory");
; #pragma unroll
;                     for (int s = 0; s < 2; ++s) {
;                         f32x4 xv = xo[s];
;                         if (mode) xv = (xv - st2[s].x) * st2[s].y * lg[bj] + lb[bj];
;                         const f32x4 zz = xv * alpha + gt[bj] * av[s];
;                         u32x2 zp; zp.x = cvt_pk_bf16(zz.x, zz.y); zp.y = cvt_pk_bf16(zz.z, zz.w);
;                         *(PG8_GAS u32x2*)(Z + off0 + (size_t)s * 8192) = zp;
;                     }
; template <class Epi, class Sched, bool ALIGN_EPI = false, bool SP2 = false>
; __device__ __forceinline__ void gemm_phase(PG8_LAS unsigned char* lds, const Gemm g, const Sched& S, const Epi& E, const int tid) {
;     ...
;         if (!has_next) break;
	ds_write_b128 v219, v[28:31]
	ds_write_b128 v220, v[24:27]
	v_pk_fma_f32 v[116:117], v[36:37], v[44:45], v[116:117]
	v_pk_fma_f32 v[118:119], v[38:39], v[46:47], v[118:119]
	v_cvt_pk_bf16_f32 v116, v116, v117
	v_cvt_pk_bf16_f32 v117, v118, v119
	global_store_dwordx2 v203, v[116:117], s[30:31] offset:256
	v_pk_fma_f32 v[112:113], v[36:37], v[40:41], v[112:113]
	v_pk_fma_f32 v[114:115], v[38:39], v[42:43], v[114:115]
	v_cvt_pk_bf16_f32 v112, v112, v113
	v_cvt_pk_bf16_f32 v113, v114, v115
	global_store_dwordx2 v203, v[112:113], s[100:101] offset:256
	s_add_u32 s30, s30, 0x8000
	s_addc_u32 s31, s31, 0
	s_add_u32 s100, s100, 0x8000
	s_addc_u32 s101, s101, 0
	s_waitcnt lgkmcnt(0)
	ds_read_b128 v[28:31], v221
	ds_read_b128 v[24:27], v221 offset:1024
	s_waitcnt vmcnt(20)
	v_pk_mul_f32 v[108:109], v[108:109], s[46:47] op_sel_hi:[1,0]
	v_pk_mul_f32 v[110:111], v[110:111], s[46:47] op_sel_hi:[1,0]
	v_pk_mul_f32 v[104:105], v[104:105], s[46:47] op_sel_hi:[1,0]
	v_pk_mul_f32 v[106:107], v[106:107], s[46:47] op_sel_hi:[1,0]
	s_waitcnt lgkmcnt(0)
	ds_write_b128 v219, v[20:23]
	ds_write_b128 v220, v[16:19]
	v_pk_fma_f32 v[108:109], v[32:33], v[28:29], v[108:109]
	v_pk_fma_f32 v[110:111], v[34:35], v[30:31], v[110:111]
	v_cvt_pk_bf16_f32 v108, v108, v109
	v_cvt_pk_bf16_f32 v109, v110, v111
	global_store_dwordx2 v203, v[108:109], s[30:31]
	v_pk_fma_f32 v[104:105], v[32:33], v[24:25], v[104:105]
	v_pk_fma_f32 v[106:107], v[34:35], v[26:27], v[106:107]
	v_cvt_pk_bf16_f32 v104, v104, v105
	v_cvt_pk_bf16_f32 v105, v106, v107
	global_store_dwordx2 v203, v[104:105], s[100:101]
	s_waitcnt lgkmcnt(0)
	ds_read_b128 v[20:23], v221
	ds_read_b128 v[16:19], v221 offset:1024
	s_waitcnt vmcnt(18)
	v_pk_mul_f32 v[100:101], v[100:101], s[46:47] op_sel_hi:[1,0]
	v_pk_mul_f32 v[102:103], v[102:103], s[46:47] op_sel_hi:[1,0]
	v_pk_mul_f32 v[96:97], v[96:97], s[46:47] op_sel_hi:[1,0]
	v_pk_mul_f32 v[98:99], v[98:99], s[46:47] op_sel_hi:[1,0]
	s_waitcnt lgkmcnt(0)
	ds_write_b128 v219, v[12:15]
	ds_write_b128 v220, v[8:11]
	v_pk_fma_f32 v[100:101], v[36:37], v[20:21], v[100:101]
	v_pk_fma_f32 v[102:103], v[38:39], v[22:23], v[102:103]
	v_cvt_pk_bf16_f32 v100, v100, v101
	v_cvt_pk_bf16_f32 v101, v102, v103
	global_store_dwordx2 v203, v[100:101], s[30:31] offset:256
	v_pk_fma_f32 v[96:97], v[36:37], v[16:17], v[96:97]
	v_pk_fma_f32 v[98:99], v[38:39], v[18:19], v[98:99]
	v_cvt_pk_bf16_f32 v96, v96, v97
	v_cvt_pk_bf16_f32 v97, v98, v99
	global_store_dwordx2 v203, v[96:97], s[100:101] offset:256
	s_add_u32 s30, s30, 0x8000
	s_addc_u32 s31, s31, 0
	s_add_u32 s100, s100, 0x8000
	s_addc_u32 s101, s101, 0
	s_waitcnt lgkmcnt(0)
	ds_read_b128 v[12:15], v221
	ds_read_b128 v[8:11], v221 offset:1024
	s_waitcnt vmcnt(16)
	v_pk_mul_f32 v[92:93], v[92:93], s[46:47] op_sel_hi:[1,0]
	v_pk_mul_f32 v[94:95], v[94:95], s[46:47] op_sel_hi:[1,0]
	v_pk_mul_f32 v[88:89], v[88:89], s[46:47] op_sel_hi:[1,0]
	v_pk_mul_f32 v[90:91], v[90:91], s[46:47] op_sel_hi:[1,0]
	s_waitcnt lgkmcnt(0)
	ds_write_b128 v219, v[4:7]
	ds_write_b128 v220, v[0:3]
	v_pk_fma_f32 v[92:93], v[32:33], v[12:13], v[92:93]
	v_pk_fma_f32 v[94:95], v[34:35], v[14:15], v[94:95]
	v_cvt_pk_bf16_f32 v92, v92, v93
	v_cvt_pk_bf16_f32 v93, v94, v95
	global_store_dwordx2 v203, v[92:93], s[30:31]
	v_pk_fma_f32 v[88:89], v[32:33], v[8:9], v[88:89]
	v_pk_fma_f32 v[90:91], v[34:35], v[10:11], v[90:91]
	v_cvt_pk_bf16_f32 v88, v88, v89
	v_cvt_pk_bf16_f32 v89, v90, v91
	global_store_dwordx2 v203, v[88:89], s[100:101]
	s_waitcnt lgkmcnt(0)
	ds_read_b128 v[4:7], v221
	ds_read_b128 v[0:3], v221 offset:1024
	s_waitcnt vmcnt(14)
	v_pk_mul_f32 v[84:85], v[84:85], s[46:47] op_sel_hi:[1,0]
	v_pk_mul_f32 v[86:87], v[86:87], s[46:47] op_sel_hi:[1,0]
	v_pk_mul_f32 v[80:81], v[80:81], s[46:47] op_sel_hi:[1,0]
	v_pk_mul_f32 v[82:83], v[82:83], s[46:47] op_sel_hi:[1,0]
	s_waitcnt lgkmcnt(0)
	v_pk_fma_f32 v[84:85], v[36:37], v[4:5], v[84:85]
	v_pk_fma_f32 v[86:87], v[38:39], v[6:7], v[86:87]
	v_cvt_pk_bf16_f32 v84, v84, v85
	v_cvt_pk_bf16_f32 v85, v86, v87
	global_store_dwordx2 v203, v[84:85], s[30:31] offset:256
	v_pk_fma_f32 v[80:81], v[36:37], v[0:1], v[80:81]
	v_pk_fma_f32 v[82:83], v[38:39], v[2:3], v[82:83]
	v_cvt_pk_bf16_f32 v80, v80, v81
	v_cvt_pk_bf16_f32 v81, v82, v83
	global_store_dwordx2 v203, v[80:81], s[100:101] offset:256
	s_and_b64 vcc, exec, s[6:7]
	s_mov_b64 s[6:7], -1
	s_cbranch_vccnz .LBB0_1293
	s_branch .Lres_hasnext
